# latent attention tile loop: double-buffered K/V LDS tile, one s_barrier per tile (same edit as the ctx loop)
# baseline (speedup 1.0000x reference)
.LBB0_512:
	s_or_b64 exec, exec, s[28:29]
	v_max_f32_e32 v89, v85, v85
	v_max_f32_e32 v90, v84, v84
	v_max_f32_e32 v89, v90, v89
	v_max_f32_e32 v90, v87, v87
	v_max_f32_e32 v91, v86, v86
	v_max_f32_e32 v90, v91, v90
	v_max_f32_e32 v91, v83, v83
	v_max_f32_e32 v92, v82, v82
	v_max_f32_e32 v91, v92, v91
	v_max3_f32 v91, v80, v81, v91
	v_max3_f32 v89, v89, v90, v91
	v_mov_b32_e32 v91, v89
	v_mov_b32_e32 v90, v89
	s_nop 1
	v_permlane16_swap_b32_e32 v91, v90
	v_max_f32_e32 v90, v91, v90
	v_add_f32_e32 v88, 0, v100
	v_add_f32_e32 v88, v101, v88
	v_add_f32_e32 v88, v102, v88
	v_add_f32_e32 v88, v103, v88
	s_waitcnt lgkmcnt(0)
	v_max_f32_e32 v90, v90, v90
	v_max_f32_e32 v89, v89, v90
	v_mov_b32_e32 v91, v89
	v_mov_b32_e32 v90, v89
	s_nop 1
	v_permlane32_swap_b32_e32 v91, v90
	v_max_f32_e32 v90, v91, v90
	v_add_f32_e32 v88, v152, v88
	v_add_f32_e32 v88, v99, v88
	v_add_f32_e32 v88, v98, v88
	v_add_f32_e32 v88, v97, v88
	s_waitcnt lgkmcnt(0)
	v_max3_f32 v89, v151, v89, v90
	v_sub_f32_e32 v84, v84, v89
	v_mul_f32_e32 v84, 0x3fb8aa3b, v84
	v_sub_f32_e32 v85, v85, v89
	v_exp_f32_e32 v84, v84
	v_mul_f32_e32 v85, 0x3fb8aa3b, v85
	v_sub_f32_e32 v86, v86, v89
	v_exp_f32_e32 v85, v85
	v_mul_f32_e32 v86, 0x3fb8aa3b, v86
	v_sub_f32_e32 v87, v87, v89
	v_exp_f32_e32 v86, v86
	v_mul_f32_e32 v87, 0x3fb8aa3b, v87
	v_sub_f32_e32 v80, v80, v89
	v_exp_f32_e32 v87, v87
	v_mul_f32_e32 v80, 0x3fb8aa3b, v80
	v_sub_f32_e32 v81, v81, v89
	v_add_f32_e32 v91, 0, v84
	v_exp_f32_e32 v92, v80
	v_mul_f32_e32 v81, 0x3fb8aa3b, v81
	v_sub_f32_e32 v82, v82, v89
	v_sub_f32_e32 v83, v83, v89
	v_add_f32_e32 v91, v85, v91
	v_exp_f32_e32 v81, v81
	v_mul_f32_e32 v82, 0x3fb8aa3b, v82
	v_mul_f32_e32 v83, 0x3fb8aa3b, v83
	v_sub_f32_e32 v90, v151, v89
	v_add_f32_e32 v91, v86, v91
	v_exp_f32_e32 v82, v82
	v_exp_f32_e32 v83, v83
	v_mul_f32_e32 v90, 0x3fb8aa3b, v90
	v_add_f32_e32 v91, v87, v91
	v_bfe_u32 v97, v86, 16, 1
	v_add_f32_e32 v80, v92, v91
	v_add3_u32 v97, v86, v97, s56
	v_exp_f32_e32 v86, v90
	v_add_f32_e32 v80, v81, v80
	v_fmac_f32_e32 v88, v126, v96
	v_add_f32_e32 v80, v82, v80
	v_bfe_u32 v91, v83, 16, 1
	v_bfe_u32 v93, v82, 16, 1
	v_bfe_u32 v94, v81, 16, 1
	v_bfe_u32 v95, v92, 16, 1
	v_bfe_u32 v96, v87, 16, 1
	v_bfe_u32 v98, v85, 16, 1
	v_bfe_u32 v99, v84, 16, 1
	v_add_f32_e32 v80, v83, v80
	v_add3_u32 v99, v84, v99, s56
	v_add3_u32 v98, v85, v98, s56
	v_add3_u32 v87, v87, v96, s56
	v_add3_u32 v84, v92, v95, s56
	v_add3_u32 v81, v81, v94, s56
	v_add3_u32 v82, v82, v93, s56
	v_add3_u32 v83, v83, v91, s56
	s_mov_b32 s0, 0x7060302
	v_perm_b32 v85, v83, v82, s0
	v_perm_b32 v84, v81, v84, s0
	v_perm_b32 v83, v87, v97, s0
	v_perm_b32 v82, v98, v99, s0
	v_pk_mul_f32 v[14:15], v[14:15], v[86:87] op_sel_hi:[1,0]
	v_pk_mul_f32 v[12:13], v[12:13], v[86:87] op_sel_hi:[1,0]
	v_pk_mul_f32 v[10:11], v[10:11], v[86:87] op_sel_hi:[1,0]
	v_pk_mul_f32 v[8:9], v[8:9], v[86:87] op_sel_hi:[1,0]
	v_pk_mul_f32 v[6:7], v[6:7], v[86:87] op_sel_hi:[1,0]
	v_pk_mul_f32 v[4:5], v[4:5], v[86:87] op_sel_hi:[1,0]
	v_pk_mul_f32 v[2:3], v[2:3], v[86:87] op_sel_hi:[1,0]
	v_pk_mul_f32 v[0:1], v[0:1], v[86:87] op_sel_hi:[1,0]
	v_mfma_f32_16x16x32_bf16 v[12:15], v[76:79], v[82:85], v[12:15]
	v_fmac_f32_e32 v80, v150, v86
	v_cmp_eq_u32_e64 s[0:1], s27, v124
	v_add_u32_e32 v142, 32, v142
	v_mfma_f32_16x16x32_bf16 v[8:11], v[72:75], v[82:85], v[8:11]
	v_add_u32_e32 v149, 32, v149
	s_or_b64 s[40:41], s[0:1], s[40:41]
	v_mov_b32_e32 v126, v88
	v_mfma_f32_16x16x32_bf16 v[4:7], v[68:71], v[82:85], v[4:7]
	v_mov_b32_e32 v150, v80
	v_mov_b32_e32 v152, v115
	v_mov_b32_e32 v151, v89
	v_mfma_f32_16x16x32_bf16 v[0:3], v[64:67], v[82:85], v[0:3]
	s_mov_b32 s26, s27
	v_xor_b32_e32 v143, 0x2000, v143
	v_xor_b32_e32 v144, 0x2000, v144
	v_xor_b32_e32 v145, 0x2000, v145
	v_xor_b32_e32 v146, 0x2000, v146
	v_xor_b32_e32 v147, 0x2000, v147
	v_xor_b32_e32 v148, 0x2000, v148
	s_andn2_b64 exec, exec, s[40:41]
	s_cbranch_execz .LBB0_523
.LBB0_513:
	v_cmp_lt_i32_e64 s[0:1], s26, v121
	s_and_saveexec_b64 s[28:29], s[0:1]
	s_cbranch_execz .LBB0_515
	v_add_u32_e32 v64, v125, v149
	v_ashrrev_i32_e32 v65, 6, v64
	v_and_b32_e32 v64, 63, v64
	v_cndmask_b32_e32 v64, v64, v65, vcc
	v_lshl_or_b32 v64, v64, 4, v106
	v_readlane_b32 s16, v250, 31
	v_ashrrev_i32_e32 v65, 31, v64
	v_readlane_b32 s17, v250, 32
	s_nop 1
	v_lshl_add_u64 v[68:69], v[64:65], 3, s[16:17]
	global_load_dwordx4 v[64:67], v[68:69], off
	s_nop 0
	global_load_dwordx4 v[68:71], v[68:69], off offset:16
	s_waitcnt vmcnt(1)
	v_mov_b32_e32 v72, v64
	s_waitcnt vmcnt(0)
	v_mul_f32_e32 v64, v62, v68
	v_mul_f32_e32 v74, v58, v69
	v_mul_f32_e32 v68, v58, v68
	v_mul_f32_e32 v76, v62, v69
	v_mov_b32_e32 v58, v63
	v_mov_b32_e32 v62, v59
	v_mov_b32_e32 v73, v66
	v_mov_b32_e32 v66, v65
	v_pk_mul_f32 v[58:59], v[58:59], v[70:71]
	v_pk_mul_f32 v[62:63], v[62:63], v[70:71]
	v_pk_mul_f32 v[78:79], v[60:61], v[66:67]
	v_pk_mul_f32 v[66:67], v[56:57], v[66:67]
	v_mov_b32_e32 v65, v58
	v_mov_b32_e32 v75, v59
	v_mov_b32_e32 v69, v62
	v_mov_b32_e32 v77, v63
	v_pk_fma_f32 v[60:61], v[60:61], v[72:73], v[66:67] neg_lo:[0,0,1] neg_hi:[0,0,1]
	v_pk_fma_f32 v[56:57], v[56:57], v[72:73], v[78:79]
	v_pk_add_f32 v[62:63], v[64:65], v[74:75] neg_lo:[0,1] neg_hi:[0,1]
	v_pk_add_f32 v[58:59], v[68:69], v[76:77]
